# 256x128 GEMM k-loops (phases 5,7,8) restaged through LDS-DMA (global_load_lds_dwordx4) into a 3-deep unpadded XOR-swizzled LDS ring, all 12 fragments read up front
# speedup vs baseline: 1.0202x; 1.0008x over previous
.LBB0_59:
	s_and_b32 s2, s2, 7
	v_readlane_b32 s4, v251, 7
	s_or_b32 s11, s2, s4
	s_lshl_b32 s10, s16, 7
	s_mul_i32 s2, s11, 0x160000
	s_add_u32 s4, s18, s2
	v_readlane_b32 s72, v250, 53
	s_addc_u32 s5, s19, 0
	s_mul_i32 s2, s16, 0xb0000
	v_readlane_b32 s84, v249, 1
	v_mov_b32_e32 v56, v200
	s_add_u32 s6, s84, s2
	s_movk_i32 s2, 0xb00
	v_ashrrev_i32_e32 v57, 2, v56
	v_lshlrev_b32_e32 v0, 3, v56
	s_waitcnt vmcnt(0)
	v_and_b32_e32 v188, 24, v0
	v_mad_i64_i32 v[0:1], s[8:9], v57, s2, 0
	v_lshlrev_b64 v[178:179], 1, v[0:1]
	v_add_u32_e32 v0, 64, v57
	v_mad_i64_i32 v[0:1], s[8:9], v0, s2, 0
	s_mul_hi_u32 s7, s10, 0x1600
	v_readlane_b32 s85, v249, 2
	v_lshlrev_b64 v[180:181], 1, v[0:1]
	v_add_u32_e32 v0, 0x80, v57
	s_addc_u32 s7, s85, s7
	v_lshlrev_b32_e32 v196, 1, v188
	v_mad_i64_i32 v[44:45], s[8:9], v0, s2, 0
	v_add_u32_e32 v0, 0xc0, v57
	v_lshl_add_u64 v[176:177], s[4:5], 0, v[196:197]
	v_mad_i64_i32 v[48:49], s[8:9], v0, s2, 0
	v_lshl_add_u64 v[182:183], s[6:7], 0, v[196:197]
	v_lshl_add_u64 v[40:41], v[176:177], 0, v[178:179]
	v_lshl_add_u64 v[42:43], v[176:177], 0, v[180:181]
	v_lshl_add_u64 v[46:47], v[44:45], 1, v[176:177]
	v_lshl_add_u64 v[50:51], v[48:49], 1, v[176:177]
	v_lshl_add_u64 v[52:53], v[182:183], 0, v[178:179]
	v_lshl_add_u64 v[54:55], v[182:183], 0, v[180:181]
	v_and_b32_e32 v192, 63, v200
	v_readfirstlane_b32 s44, v200
	v_lshrrev_b32_e32 v193, 2, v192
	v_and_b32_e32 v194, 3, v192
	v_lshrrev_b32_e32 v201, 4, v192
	s_lshr_b32 s44, s44, 6
	v_xor_b32_e32 v206, v194, v201
	v_lshlrev_b32_e32 v206, 4, v206
	s_lshl_b32 s32, s44, 6
	v_add_u32_e32 v212, s32, v193
	v_mul_u32_u24_e32 v212, 0x1600, v212
	v_add_u32_e32 v234, v212, v206
	v_add_u32_e32 v235, 0x16000, v234
	v_add_u32_e32 v236, 0x2c000, v234
	v_add_u32_e32 v237, 0x42000, v234
	s_lshl_b32 s32, s44, 5
	v_add_u32_e32 v212, s32, v193
	v_mul_u32_u24_e32 v212, 0x1600, v212
	v_add_u32_e32 v238, v212, v206
	v_add_u32_e32 v239, 0x16000, v238
	v_and_b32_e32 v193, 31, v192
	v_lshrrev_b32_e32 v194, 5, v192
	v_bfe_u32 v201, v192, 2, 2
	v_xor_b32_e32 v206, v194, v201
	v_lshlrev_b32_e32 v206, 4, v206
	v_lshl_add_u32 v206, v193, 6, v206
	s_lshr_b32 s32, s44, 1
	s_lshl_b32 s32, s32, 13
	v_add_u32_e32 v240, s32, v206
	v_xor_b32_e32 v241, 32, v240
	s_and_b32 s32, s44, 1
	s_lshl_b32 s32, s32, 12
	s_add_u32 s32, s32, 0x4000
	v_add_u32_e32 v242, s32, v206
	v_xor_b32_e32 v243, 32, v242
	s_lshl_b32 s46, s44, 12
	s_lshl_b32 s47, s44, 11
	s_add_u32 s47, s47, 0x4000
	s_mov_b32 s40, s4
	s_mov_b32 s41, s5
	s_mov_b32 s42, s6
	s_mov_b32 s43, s7
	s_add_u32 m0, s46, 0x0
	s_nop 0
	global_load_lds_dwordx4 v234, s[40:41]
	s_add_u32 m0, m0, 0x400
	s_nop 0
	global_load_lds_dwordx4 v235, s[40:41]
	s_add_u32 m0, m0, 0x400
	s_nop 0
	global_load_lds_dwordx4 v236, s[40:41]
	s_add_u32 m0, m0, 0x400
	s_nop 0
	global_load_lds_dwordx4 v237, s[40:41]
	s_add_u32 m0, s47, 0x0
	s_nop 0
	global_load_lds_dwordx4 v238, s[42:43]
	s_add_u32 m0, m0, 0x400
	s_nop 0
	global_load_lds_dwordx4 v239, s[42:43]
	s_add_u32 s40, s40, 64
	s_addc_u32 s41, s41, 0
	s_add_u32 s42, s42, 64
	s_addc_u32 s43, s43, 0
	s_add_u32 m0, s46, 0x6000
	s_nop 0
	global_load_lds_dwordx4 v234, s[40:41]
	s_add_u32 m0, m0, 0x400
	s_nop 0
	global_load_lds_dwordx4 v235, s[40:41]
	s_add_u32 m0, m0, 0x400
	s_nop 0
	global_load_lds_dwordx4 v236, s[40:41]
	s_add_u32 m0, m0, 0x400
	s_nop 0
	global_load_lds_dwordx4 v237, s[40:41]
	s_add_u32 m0, s47, 0x6000
	s_nop 0
	global_load_lds_dwordx4 v238, s[42:43]
	s_add_u32 m0, m0, 0x400
	s_nop 0
	global_load_lds_dwordx4 v239, s[42:43]
	s_add_u32 s40, s40, 64
	s_addc_u32 s41, s41, 0
	s_add_u32 s42, s42, 64
	s_addc_u32 s43, s43, 0
	s_mov_b32 s45, 0xc000
	s_mov_b32 s49, 0
	v_and_b32_e32 v58, 0xfffff9f, v56
	v_lshrrev_b32_e32 v59, 1, v56
	v_and_b32_e32 v56, 0x5f, v56
	s_movk_i32 s2, 0x50
	v_and_b32_e32 v59, 16, v59
	v_mad_u32_u24 v56, v56, s2, 0
	v_mul_lo_u32 v57, v57, s2
	v_mul_lo_u32 v58, v58, s2
	v_add_u32_e32 v189, v56, v59
	v_add_u32_e32 v56, 0, v196
	v_mov_b32_e32 v0, 0
	v_add_u32_e32 v58, 0, v58
	v_add_u32_e32 v191, v56, v57
	s_mov_b32 s17, 64
	s_mov_b32 s18, 0
	v_mov_b32_e32 v1, v0
	v_mov_b32_e32 v2, v0
	v_mov_b32_e32 v3, v0
	v_mov_b32_e32 v4, v0
	v_mov_b32_e32 v5, v0
	v_mov_b32_e32 v6, v0
	v_mov_b32_e32 v7, v0
	v_mov_b32_e32 v8, v0
	v_mov_b32_e32 v9, v0
	v_mov_b32_e32 v10, v0
	v_mov_b32_e32 v11, v0
	v_mov_b32_e32 v12, v0
	v_mov_b32_e32 v13, v0
	v_mov_b32_e32 v14, v0
	v_mov_b32_e32 v15, v0
	v_lshlrev_b64 v[184:185], 1, v[44:45]
	v_lshlrev_b64 v[186:187], 1, v[48:49]
	v_add_u32_e32 v190, v58, v59
	v_mov_b32_e32 v40, v0
	v_mov_b32_e32 v41, v0
	v_mov_b32_e32 v42, v0
	v_mov_b32_e32 v43, v0
	v_mov_b32_e32 v44, v0
	v_mov_b32_e32 v45, v0
	v_mov_b32_e32 v46, v0
	v_mov_b32_e32 v47, v0
	v_mov_b32_e32 v16, v0
	v_mov_b32_e32 v17, v0
	v_mov_b32_e32 v18, v0
	v_mov_b32_e32 v19, v0
	v_mov_b32_e32 v20, v0
	v_mov_b32_e32 v21, v0
	v_mov_b32_e32 v22, v0
	v_mov_b32_e32 v23, v0
	v_mov_b32_e32 v24, v0
	v_mov_b32_e32 v25, v0
	v_mov_b32_e32 v26, v0
	v_mov_b32_e32 v27, v0
	v_mov_b32_e32 v28, v0
	v_mov_b32_e32 v29, v0
	v_mov_b32_e32 v30, v0
	v_mov_b32_e32 v31, v0
	v_mov_b32_e32 v32, v0
	v_mov_b32_e32 v33, v0
	v_mov_b32_e32 v34, v0
	v_mov_b32_e32 v35, v0
	v_mov_b32_e32 v36, v0
	v_mov_b32_e32 v37, v0
	v_mov_b32_e32 v38, v0
	v_mov_b32_e32 v39, v0
	v_mov_b32_e32 v48, v0
	v_mov_b32_e32 v49, v0
	v_mov_b32_e32 v50, v0
	v_mov_b32_e32 v51, v0
	v_mov_b32_e32 v52, v0
	v_mov_b32_e32 v53, v0
	v_mov_b32_e32 v54, v0
	v_mov_b32_e32 v55, v0
	v_mov_b32_e32 v56, v0
	v_mov_b32_e32 v57, v0
	v_mov_b32_e32 v58, v0
	v_mov_b32_e32 v59, v0
	v_mov_b32_e32 v60, v0
	v_mov_b32_e32 v61, v0
	v_mov_b32_e32 v62, v0
	v_mov_b32_e32 v63, v0
	v_mov_b32_e32 v64, v0
	v_mov_b32_e32 v65, v0
	v_mov_b32_e32 v66, v0
	v_mov_b32_e32 v67, v0
	v_mov_b32_e32 v68, v0
	v_mov_b32_e32 v69, v0
	v_mov_b32_e32 v70, v0
	v_mov_b32_e32 v71, v0
	v_mov_b32_e32 v72, v0
	v_mov_b32_e32 v73, v0
	v_mov_b32_e32 v74, v0
	v_mov_b32_e32 v75, v0
	v_mov_b32_e32 v76, v0
	v_mov_b32_e32 v77, v0
	v_mov_b32_e32 v78, v0
	v_mov_b32_e32 v79, v0
	v_mov_b32_e32 v80, v0
	v_mov_b32_e32 v81, v0
	v_mov_b32_e32 v82, v0
	v_mov_b32_e32 v83, v0
	v_mov_b32_e32 v84, v0
	v_mov_b32_e32 v85, v0
	v_mov_b32_e32 v86, v0
	v_mov_b32_e32 v87, v0
	v_mov_b32_e32 v88, v0
	v_mov_b32_e32 v89, v0
	v_mov_b32_e32 v90, v0
	v_mov_b32_e32 v91, v0
	v_mov_b32_e32 v92, v0
	v_mov_b32_e32 v93, v0
	v_mov_b32_e32 v94, v0
	v_mov_b32_e32 v95, v0
	v_mov_b32_e32 v96, v0
	v_mov_b32_e32 v97, v0
	v_mov_b32_e32 v98, v0
	v_mov_b32_e32 v99, v0
	v_mov_b32_e32 v100, v0
	v_mov_b32_e32 v101, v0
	v_mov_b32_e32 v102, v0
	v_mov_b32_e32 v103, v0
	v_mov_b32_e32 v104, v0
	v_mov_b32_e32 v105, v0
	v_mov_b32_e32 v106, v0
	v_mov_b32_e32 v107, v0
	v_mov_b32_e32 v108, v0
	v_mov_b32_e32 v109, v0
	v_mov_b32_e32 v110, v0
	v_mov_b32_e32 v111, v0
	v_mov_b32_e32 v112, v0
	v_mov_b32_e32 v113, v0
	v_mov_b32_e32 v114, v0
	v_mov_b32_e32 v115, v0
	v_mov_b32_e32 v116, v0
	v_mov_b32_e32 v117, v0
	v_mov_b32_e32 v118, v0
	v_mov_b32_e32 v119, v0
	v_mov_b32_e32 v120, v0
	v_mov_b32_e32 v121, v0
	v_mov_b32_e32 v122, v0
	v_mov_b32_e32 v123, v0
	v_mov_b32_e32 v124, v0
	v_mov_b32_e32 v125, v0
	v_mov_b32_e32 v126, v0
	v_mov_b32_e32 v127, v0
	v_readlane_b32 s73, v250, 54
	v_readlane_b32 s74, v250, 55
	v_readlane_b32 s75, v250, 56
	v_readlane_b32 s76, v250, 57
	v_readlane_b32 s77, v250, 58
	v_readlane_b32 s78, v250, 59
	v_readlane_b32 s79, v250, 60
	v_readlane_b32 s80, v250, 61
	v_readlane_b32 s81, v250, 62
	v_readlane_b32 s82, v250, 63
	v_readlane_b32 s83, v249, 0
	v_readlane_b32 s86, v249, 3
	v_readlane_b32 s87, v249, 4
	s_waitcnt vmcnt(6)
	s_waitcnt lgkmcnt(0)
	s_barrier
	s_branch .LBB0_61
.LBB0_61:
	ds_read_b128 v[128:131], v242
	ds_read_b128 v[136:139], v240
	ds_read_b128 v[132:135], v242 offset:2048
	ds_read_b128 v[140:143], v240 offset:2048
	ds_read_b128 v[144:147], v240 offset:4096
	ds_read_b128 v[148:151], v240 offset:6144
	ds_read_b128 v[152:155], v243
	ds_read_b128 v[156:159], v243 offset:2048
	ds_read_b128 v[160:163], v241
	ds_read_b128 v[164:167], v241 offset:2048
	ds_read_b128 v[168:171], v241 offset:4096
	ds_read_b128 v[172:175], v241 offset:6144
	s_add_u32 m0, s46, s45
	s_waitcnt lgkmcnt(10)
	v_mfma_f32_32x32x16_bf16 v[112:127], v[128:131], v[136:139], v[112:127]
	s_waitcnt lgkmcnt(9)
	v_mfma_f32_32x32x16_bf16 v[96:111], v[132:135], v[136:139], v[96:111]
	global_load_lds_dwordx4 v234, s[40:41]
	s_add_u32 m0, m0, 0x400
	s_waitcnt lgkmcnt(8)
	v_mfma_f32_32x32x16_bf16 v[80:95], v[128:131], v[140:143], v[80:95]
	v_mfma_f32_32x32x16_bf16 v[64:79], v[132:135], v[140:143], v[64:79]
	global_load_lds_dwordx4 v235, s[40:41]
	s_add_u32 m0, m0, 0x400
	s_waitcnt lgkmcnt(7)
	v_mfma_f32_32x32x16_bf16 v[48:63], v[128:131], v[144:147], v[48:63]
	v_mfma_f32_32x32x16_bf16 v[32:47], v[132:135], v[144:147], v[32:47]
	global_load_lds_dwordx4 v236, s[40:41]
	s_add_u32 m0, m0, 0x400
	s_waitcnt lgkmcnt(6)
	v_mfma_f32_32x32x16_bf16 v[16:31], v[128:131], v[148:151], v[16:31]
	v_mfma_f32_32x32x16_bf16 v[0:15], v[132:135], v[148:151], v[0:15]
	global_load_lds_dwordx4 v237, s[40:41]
	s_add_u32 m0, s47, s45
	s_waitcnt lgkmcnt(3)
	v_mfma_f32_32x32x16_bf16 v[112:127], v[152:155], v[160:163], v[112:127]
	v_mfma_f32_32x32x16_bf16 v[96:111], v[156:159], v[160:163], v[96:111]
	global_load_lds_dwordx4 v238, s[42:43]
	s_add_u32 m0, m0, 0x400
	s_waitcnt lgkmcnt(2)
	v_mfma_f32_32x32x16_bf16 v[80:95], v[152:155], v[164:167], v[80:95]
	v_mfma_f32_32x32x16_bf16 v[64:79], v[156:159], v[164:167], v[64:79]
	global_load_lds_dwordx4 v239, s[42:43]
	s_waitcnt lgkmcnt(1)
	v_mfma_f32_32x32x16_bf16 v[48:63], v[152:155], v[168:171], v[48:63]
	s_mov_b32 s32, 0x6000
	s_cmp_eq_u32 s49, 0xc000
	s_cselect_b32 s32, 0xffff4000, s32
	s_add_u32 s49, s49, s32
	v_add_u32_e32 v240, s32, v240
	v_add_u32_e32 v241, s32, v241
	v_add_u32_e32 v242, s32, v242
	v_add_u32_e32 v243, s32, v243
	s_add_u32 s45, s45, 0x6000
	s_cmp_eq_u32 s45, 0x12000
	s_cselect_b32 s45, 0, s45
	s_add_u32 s40, s40, 64
	s_addc_u32 s41, s41, 0
	s_add_u32 s42, s42, 64
	s_addc_u32 s43, s43, 0
	v_mfma_f32_32x32x16_bf16 v[32:47], v[156:159], v[168:171], v[32:47]
	s_waitcnt lgkmcnt(0)
	v_mfma_f32_32x32x16_bf16 v[16:31], v[152:155], v[172:175], v[16:31]
	v_mfma_f32_32x32x16_bf16 v[0:15], v[156:159], v[172:175], v[0:15]
	s_add_u32 s18, s18, 1
	s_waitcnt vmcnt(6)
	s_cmp_lt_u32 s18, 86
	s_barrier
	s_cbranch_scc1 .LBB0_61
.Lp8_tail:
	ds_read_b128 v[128:131], v242
	ds_read_b128 v[136:139], v240
	ds_read_b128 v[132:135], v242 offset:2048
	ds_read_b128 v[140:143], v240 offset:2048
	ds_read_b128 v[144:147], v240 offset:4096
	ds_read_b128 v[148:151], v240 offset:6144
	ds_read_b128 v[152:155], v243
	ds_read_b128 v[156:159], v243 offset:2048
	ds_read_b128 v[160:163], v241
	ds_read_b128 v[164:167], v241 offset:2048
	ds_read_b128 v[168:171], v241 offset:4096
	ds_read_b128 v[172:175], v241 offset:6144
	s_waitcnt lgkmcnt(10)
	v_mfma_f32_32x32x16_bf16 v[112:127], v[128:131], v[136:139], v[112:127]
	s_waitcnt lgkmcnt(9)
	v_mfma_f32_32x32x16_bf16 v[96:111], v[132:135], v[136:139], v[96:111]
	s_waitcnt lgkmcnt(8)
	v_mfma_f32_32x32x16_bf16 v[80:95], v[128:131], v[140:143], v[80:95]
	v_mfma_f32_32x32x16_bf16 v[64:79], v[132:135], v[140:143], v[64:79]
	s_waitcnt lgkmcnt(7)
	v_mfma_f32_32x32x16_bf16 v[48:63], v[128:131], v[144:147], v[48:63]
	v_mfma_f32_32x32x16_bf16 v[32:47], v[132:135], v[144:147], v[32:47]
	s_waitcnt lgkmcnt(6)
	v_mfma_f32_32x32x16_bf16 v[16:31], v[128:131], v[148:151], v[16:31]
	v_mfma_f32_32x32x16_bf16 v[0:15], v[132:135], v[148:151], v[0:15]
	s_waitcnt lgkmcnt(3)
	v_mfma_f32_32x32x16_bf16 v[112:127], v[152:155], v[160:163], v[112:127]
	v_mfma_f32_32x32x16_bf16 v[96:111], v[156:159], v[160:163], v[96:111]
	s_waitcnt lgkmcnt(2)
	v_mfma_f32_32x32x16_bf16 v[80:95], v[152:155], v[164:167], v[80:95]
	v_mfma_f32_32x32x16_bf16 v[64:79], v[156:159], v[164:167], v[64:79]
	s_waitcnt lgkmcnt(1)
	v_mfma_f32_32x32x16_bf16 v[48:63], v[152:155], v[168:171], v[48:63]
	s_mov_b32 s32, 0x6000
	s_cmp_eq_u32 s49, 0xc000
	s_cselect_b32 s32, 0xffff4000, s32
	s_add_u32 s49, s49, s32
	v_add_u32_e32 v240, s32, v240
	v_add_u32_e32 v241, s32, v241
	v_add_u32_e32 v242, s32, v242
	v_add_u32_e32 v243, s32, v243
	v_mfma_f32_32x32x16_bf16 v[32:47], v[156:159], v[168:171], v[32:47]
	s_waitcnt lgkmcnt(0)
	v_mfma_f32_32x32x16_bf16 v[16:31], v[152:155], v[172:175], v[16:31]
	v_mfma_f32_32x32x16_bf16 v[0:15], v[156:159], v[172:175], v[0:15]
	s_add_u32 s18, s18, 1
	s_waitcnt vmcnt(0)
	s_cmp_lt_u32 s18, 88
	s_barrier
	s_cbranch_scc1 .Lp8_tail
	s_branch .LBB0_63

.LBB0_75:
	s_and_b32 s4, s2, 7
	v_readlane_b32 s5, v251, 7
	s_or_b32 s11, s4, s5
	v_readlane_b32 s16, v250, 53
	s_lshr_b32 s10, s2, 3
	s_lshl_b32 s2, s11, 19
	v_readlane_b32 s22, v250, 59
	v_mov_b32_e32 v13, v200
	v_readlane_b32 s23, v250, 60
	s_add_u32 s4, s22, s2
	v_readlane_b32 s26, v250, 63
	v_ashrrev_i32_e32 v38, 2, v13
	v_lshlrev_b32_e32 v0, 3, v13
	s_addc_u32 s5, s23, 0
	s_lshl_b32 s2, s10, 18
	s_waitcnt vmcnt(0)
	v_and_b32_e32 v188, 24, v0
	v_add_u32_e32 v46, 0x80, v38
	v_readlane_b32 s27, v249, 0
	s_add_u32 s6, s26, s2
	v_lshlrev_b32_e32 v196, 1, v188
	v_add_u32_e32 v42, 64, v38
	v_ashrrev_i32_e32 v47, 31, v46
	v_add_u32_e32 v50, 0xc0, v38
	s_addc_u32 s7, s27, 0
	v_lshl_add_u64 v[176:177], s[4:5], 0, v[196:197]
	v_ashrrev_i32_e32 v39, 31, v38
	v_ashrrev_i32_e32 v43, 31, v42
	v_lshlrev_b64 v[4:5], 11, v[46:47]
	v_ashrrev_i32_e32 v51, 31, v50
	v_lshlrev_b64 v[0:1], 11, v[38:39]
	v_lshlrev_b64 v[2:3], 11, v[42:43]
	v_lshl_add_u64 v[48:49], v[176:177], 0, v[4:5]
	v_lshlrev_b64 v[4:5], 11, v[50:51]
	v_lshl_add_u64 v[178:179], s[6:7], 0, v[196:197]
	v_lshl_add_u64 v[40:41], v[176:177], 0, v[0:1]
	v_lshl_add_u64 v[44:45], v[176:177], 0, v[2:3]
	v_lshl_add_u64 v[52:53], v[176:177], 0, v[4:5]
	v_lshl_add_u64 v[54:55], v[178:179], 0, v[0:1]
	v_lshl_add_u64 v[56:57], v[178:179], 0, v[2:3]
	v_and_b32_e32 v192, 63, v200
	v_readfirstlane_b32 s44, v200
	v_lshrrev_b32_e32 v193, 2, v192
	v_and_b32_e32 v194, 3, v192
	v_lshrrev_b32_e32 v201, 4, v192
	s_lshr_b32 s44, s44, 6
	v_xor_b32_e32 v206, v194, v201
	v_lshlrev_b32_e32 v206, 4, v206
	s_lshl_b32 s32, s44, 6
	v_add_u32_e32 v212, s32, v193
	v_lshlrev_b32_e32 v212, 11, v212
	v_add_u32_e32 v234, v212, v206
	v_add_u32_e32 v235, 0x8000, v234
	v_add_u32_e32 v236, 0x10000, v234
	v_add_u32_e32 v237, 0x18000, v234
	s_lshl_b32 s32, s44, 5
	v_add_u32_e32 v212, s32, v193
	v_lshlrev_b32_e32 v212, 11, v212
	v_add_u32_e32 v238, v212, v206
	v_add_u32_e32 v239, 0x8000, v238
	v_and_b32_e32 v193, 31, v192
	v_lshrrev_b32_e32 v194, 5, v192
	v_bfe_u32 v201, v192, 2, 2
	v_xor_b32_e32 v206, v194, v201
	v_lshlrev_b32_e32 v206, 4, v206
	v_lshl_add_u32 v206, v193, 6, v206
	s_lshr_b32 s32, s44, 1
	s_lshl_b32 s32, s32, 13
	v_add_u32_e32 v240, s32, v206
	v_xor_b32_e32 v241, 32, v240
	s_and_b32 s32, s44, 1
	s_lshl_b32 s32, s32, 12
	s_add_u32 s32, s32, 0x4000
	v_add_u32_e32 v242, s32, v206
	v_xor_b32_e32 v243, 32, v242
	s_lshl_b32 s46, s44, 12
	s_lshl_b32 s47, s44, 11
	s_add_u32 s47, s47, 0x4000
	s_mov_b32 s40, s4
	s_mov_b32 s41, s5
	s_mov_b32 s42, s6
	s_mov_b32 s43, s7
	s_add_u32 m0, s46, 0x0
	s_nop 0
	global_load_lds_dwordx4 v234, s[40:41]
	s_add_u32 m0, m0, 0x400
	s_nop 0
	global_load_lds_dwordx4 v235, s[40:41]
	s_add_u32 m0, m0, 0x400
	s_nop 0
	global_load_lds_dwordx4 v236, s[40:41]
	s_add_u32 m0, m0, 0x400
	s_nop 0
	global_load_lds_dwordx4 v237, s[40:41]
	s_add_u32 m0, s47, 0x0
	s_nop 0
	global_load_lds_dwordx4 v238, s[42:43]
	s_add_u32 m0, m0, 0x400
	s_nop 0
	global_load_lds_dwordx4 v239, s[42:43]
	s_add_u32 s40, s40, 64
	s_addc_u32 s41, s41, 0
	s_add_u32 s42, s42, 64
	s_addc_u32 s43, s43, 0
	s_add_u32 m0, s46, 0x6000
	s_nop 0
	global_load_lds_dwordx4 v234, s[40:41]
	s_add_u32 m0, m0, 0x400
	s_nop 0
	global_load_lds_dwordx4 v235, s[40:41]
	s_add_u32 m0, m0, 0x400
	s_nop 0
	global_load_lds_dwordx4 v236, s[40:41]
	s_add_u32 m0, m0, 0x400
	s_nop 0
	global_load_lds_dwordx4 v237, s[40:41]
	s_add_u32 m0, s47, 0x6000
	s_nop 0
	global_load_lds_dwordx4 v238, s[42:43]
	s_add_u32 m0, m0, 0x400
	s_nop 0
	global_load_lds_dwordx4 v239, s[42:43]
	s_add_u32 s40, s40, 64
	s_addc_u32 s41, s41, 0
	s_add_u32 s42, s42, 64
	s_addc_u32 s43, s43, 0
	s_mov_b32 s45, 0xc000
	s_mov_b32 s49, 0
	v_and_b32_e32 v58, 0xfffff9f, v13
	v_lshrrev_b32_e32 v59, 1, v13
	v_and_b32_e32 v13, 0x5f, v13
	s_movk_i32 s2, 0x50
	v_and_b32_e32 v59, 16, v59
	v_mad_u32_u24 v13, v13, s2, 0
	v_mul_lo_u32 v60, v38, s2
	v_mul_lo_u32 v58, v58, s2
	v_add_u32_e32 v189, v13, v59
	v_add_u32_e32 v13, 0, v196
	v_readlane_b32 s17, v250, 54
	v_mov_b32_e32 v0, 0
	v_lshlrev_b64 v[38:39], 10, v[38:39]
	v_add_u32_e32 v58, 0, v58
	v_lshlrev_b64 v[42:43], 10, v[42:43]
	v_lshlrev_b64 v[46:47], 10, v[46:47]
	v_lshlrev_b64 v[50:51], 10, v[50:51]
	v_add_u32_e32 v191, v13, v60
	s_mov_b32 s16, 64
	s_mov_b32 s17, 0
	v_mov_b32_e32 v1, v0
	v_mov_b32_e32 v2, v0
	v_mov_b32_e32 v3, v0
	v_mov_b32_e32 v4, v0
	v_mov_b32_e32 v5, v0
	v_mov_b32_e32 v6, v0
	v_mov_b32_e32 v7, v0
	v_mov_b32_e32 v8, v0
	v_mov_b32_e32 v9, v0
	v_mov_b32_e32 v10, v0
	v_mov_b32_e32 v11, v0
	v_mov_b32_e32 v12, v0
	v_lshlrev_b64 v[180:181], 1, v[38:39]
	v_add_u32_e32 v190, v58, v59
	v_lshlrev_b64 v[182:183], 1, v[42:43]
	v_lshlrev_b64 v[184:185], 1, v[46:47]
	v_lshlrev_b64 v[186:187], 1, v[50:51]
	v_mov_b32_e32 v13, v0
	v_mov_b32_e32 v38, v0
	v_mov_b32_e32 v39, v0
	v_mov_b32_e32 v14, v0
	v_mov_b32_e32 v15, v0
	v_mov_b32_e32 v16, v0
	v_mov_b32_e32 v17, v0
	v_mov_b32_e32 v18, v0
	v_mov_b32_e32 v19, v0
	v_mov_b32_e32 v20, v0
	v_mov_b32_e32 v21, v0
	v_mov_b32_e32 v22, v0
	v_mov_b32_e32 v23, v0
	v_mov_b32_e32 v24, v0
	v_mov_b32_e32 v25, v0
	v_mov_b32_e32 v26, v0
	v_mov_b32_e32 v27, v0
	v_mov_b32_e32 v28, v0
	v_mov_b32_e32 v29, v0
	v_mov_b32_e32 v30, v0
	v_mov_b32_e32 v31, v0
	v_mov_b32_e32 v32, v0
	v_mov_b32_e32 v33, v0
	v_mov_b32_e32 v34, v0
	v_mov_b32_e32 v35, v0
	v_mov_b32_e32 v36, v0
	v_mov_b32_e32 v37, v0
	v_mov_b32_e32 v40, v0
	v_mov_b32_e32 v41, v0
	v_mov_b32_e32 v42, v0
	v_mov_b32_e32 v43, v0
	v_mov_b32_e32 v44, v0
	v_mov_b32_e32 v45, v0
	v_mov_b32_e32 v46, v0
	v_mov_b32_e32 v47, v0
	v_mov_b32_e32 v48, v0
	v_mov_b32_e32 v49, v0
	v_mov_b32_e32 v50, v0
	v_mov_b32_e32 v51, v0
	v_mov_b32_e32 v52, v0
	v_mov_b32_e32 v53, v0
	v_mov_b32_e32 v54, v0
	v_mov_b32_e32 v55, v0
	v_mov_b32_e32 v56, v0
	v_mov_b32_e32 v57, v0
	v_mov_b32_e32 v58, v0
	v_mov_b32_e32 v59, v0
	v_mov_b32_e32 v60, v0
	v_mov_b32_e32 v61, v0
	v_mov_b32_e32 v62, v0
	v_mov_b32_e32 v63, v0
	v_mov_b32_e32 v64, v0
	v_mov_b32_e32 v65, v0
	v_mov_b32_e32 v66, v0
	v_mov_b32_e32 v67, v0
	v_mov_b32_e32 v68, v0
	v_mov_b32_e32 v69, v0
	v_mov_b32_e32 v70, v0
	v_mov_b32_e32 v71, v0
	v_mov_b32_e32 v72, v0
	v_mov_b32_e32 v73, v0
	v_mov_b32_e32 v74, v0
	v_mov_b32_e32 v75, v0
	v_mov_b32_e32 v76, v0
	v_mov_b32_e32 v77, v0
	v_mov_b32_e32 v78, v0
	v_mov_b32_e32 v79, v0
	v_mov_b32_e32 v80, v0
	v_mov_b32_e32 v81, v0
	v_mov_b32_e32 v82, v0
	v_mov_b32_e32 v83, v0
	v_mov_b32_e32 v84, v0
	v_mov_b32_e32 v85, v0
	v_mov_b32_e32 v86, v0
	v_mov_b32_e32 v87, v0
	v_mov_b32_e32 v88, v0
	v_mov_b32_e32 v89, v0
	v_mov_b32_e32 v90, v0
	v_mov_b32_e32 v91, v0
	v_mov_b32_e32 v92, v0
	v_mov_b32_e32 v93, v0
	v_mov_b32_e32 v94, v0
	v_mov_b32_e32 v95, v0
	v_mov_b32_e32 v96, v0
	v_mov_b32_e32 v97, v0
	v_mov_b32_e32 v98, v0
	v_mov_b32_e32 v99, v0
	v_mov_b32_e32 v100, v0
	v_mov_b32_e32 v101, v0
	v_mov_b32_e32 v102, v0
	v_mov_b32_e32 v103, v0
	v_mov_b32_e32 v104, v0
	v_mov_b32_e32 v105, v0
	v_mov_b32_e32 v106, v0
	v_mov_b32_e32 v107, v0
	v_mov_b32_e32 v108, v0
	v_mov_b32_e32 v109, v0
	v_mov_b32_e32 v110, v0
	v_mov_b32_e32 v111, v0
	v_mov_b32_e32 v112, v0
	v_mov_b32_e32 v113, v0
	v_mov_b32_e32 v114, v0
	v_mov_b32_e32 v115, v0
	v_mov_b32_e32 v116, v0
	v_mov_b32_e32 v117, v0
	v_mov_b32_e32 v118, v0
	v_mov_b32_e32 v119, v0
	v_mov_b32_e32 v120, v0
	v_mov_b32_e32 v121, v0
	v_mov_b32_e32 v122, v0
	v_mov_b32_e32 v123, v0
	v_mov_b32_e32 v124, v0
	v_mov_b32_e32 v125, v0
	v_mov_b32_e32 v126, v0
	v_mov_b32_e32 v127, v0
	v_readlane_b32 s18, v250, 55
	v_readlane_b32 s19, v250, 56
	v_readlane_b32 s20, v250, 57
	v_readlane_b32 s21, v250, 58
	v_readlane_b32 s24, v250, 61
	v_readlane_b32 s25, v250, 62
	v_readlane_b32 s28, v249, 1
	v_readlane_b32 s29, v249, 2
	v_readlane_b32 s30, v249, 3
	v_readlane_b32 s31, v249, 4
	s_waitcnt vmcnt(6)
	s_waitcnt lgkmcnt(0)
	s_barrier
	s_branch .LBB0_77
.LBB0_77:
	ds_read_b128 v[128:131], v242
	ds_read_b128 v[136:139], v240
	ds_read_b128 v[132:135], v242 offset:2048
	ds_read_b128 v[140:143], v240 offset:2048
	ds_read_b128 v[144:147], v240 offset:4096
	ds_read_b128 v[148:151], v240 offset:6144
	ds_read_b128 v[152:155], v243
	ds_read_b128 v[156:159], v243 offset:2048
	ds_read_b128 v[160:163], v241
	ds_read_b128 v[164:167], v241 offset:2048
	ds_read_b128 v[168:171], v241 offset:4096
	ds_read_b128 v[172:175], v241 offset:6144
	s_add_u32 m0, s46, s45
	s_waitcnt lgkmcnt(10)
	v_mfma_f32_32x32x16_bf16 v[112:127], v[128:131], v[136:139], v[112:127]
	s_waitcnt lgkmcnt(9)
	v_mfma_f32_32x32x16_bf16 v[96:111], v[132:135], v[136:139], v[96:111]
	global_load_lds_dwordx4 v234, s[40:41]
	s_add_u32 m0, m0, 0x400
	s_waitcnt lgkmcnt(8)
	v_mfma_f32_32x32x16_bf16 v[80:95], v[128:131], v[140:143], v[80:95]
	v_mfma_f32_32x32x16_bf16 v[64:79], v[132:135], v[140:143], v[64:79]
	global_load_lds_dwordx4 v235, s[40:41]
	s_add_u32 m0, m0, 0x400
	s_waitcnt lgkmcnt(7)
	v_mfma_f32_32x32x16_bf16 v[48:63], v[128:131], v[144:147], v[48:63]
	v_mfma_f32_32x32x16_bf16 v[32:47], v[132:135], v[144:147], v[32:47]
	global_load_lds_dwordx4 v236, s[40:41]
	s_add_u32 m0, m0, 0x400
	s_waitcnt lgkmcnt(6)
	v_mfma_f32_32x32x16_bf16 v[16:31], v[128:131], v[148:151], v[16:31]
	v_mfma_f32_32x32x16_bf16 v[0:15], v[132:135], v[148:151], v[0:15]
	global_load_lds_dwordx4 v237, s[40:41]
	s_add_u32 m0, s47, s45
	s_waitcnt lgkmcnt(3)
	v_mfma_f32_32x32x16_bf16 v[112:127], v[152:155], v[160:163], v[112:127]
	v_mfma_f32_32x32x16_bf16 v[96:111], v[156:159], v[160:163], v[96:111]
	global_load_lds_dwordx4 v238, s[42:43]
	s_add_u32 m0, m0, 0x400
	s_waitcnt lgkmcnt(2)
	v_mfma_f32_32x32x16_bf16 v[80:95], v[152:155], v[164:167], v[80:95]
	v_mfma_f32_32x32x16_bf16 v[64:79], v[156:159], v[164:167], v[64:79]
	global_load_lds_dwordx4 v239, s[42:43]
	s_waitcnt lgkmcnt(1)
	v_mfma_f32_32x32x16_bf16 v[48:63], v[152:155], v[168:171], v[48:63]
	s_mov_b32 s32, 0x6000
	s_cmp_eq_u32 s49, 0xc000
	s_cselect_b32 s32, 0xffff4000, s32
	s_add_u32 s49, s49, s32
	v_add_u32_e32 v240, s32, v240
	v_add_u32_e32 v241, s32, v241
	v_add_u32_e32 v242, s32, v242
	v_add_u32_e32 v243, s32, v243
	s_add_u32 s45, s45, 0x6000
	s_cmp_eq_u32 s45, 0x12000
	s_cselect_b32 s45, 0, s45
	s_add_u32 s40, s40, 64
	s_addc_u32 s41, s41, 0
	s_add_u32 s42, s42, 64
	s_addc_u32 s43, s43, 0
	v_mfma_f32_32x32x16_bf16 v[32:47], v[156:159], v[168:171], v[32:47]
	s_waitcnt lgkmcnt(0)
	v_mfma_f32_32x32x16_bf16 v[16:31], v[152:155], v[172:175], v[16:31]
	v_mfma_f32_32x32x16_bf16 v[0:15], v[156:159], v[172:175], v[0:15]
	s_add_u32 s17, s17, 1
	s_waitcnt vmcnt(6)
	s_cmp_lt_u32 s17, 30
	s_barrier
	s_cbranch_scc1 .LBB0_77
.Lp7_tail:
	ds_read_b128 v[128:131], v242
	ds_read_b128 v[136:139], v240
	ds_read_b128 v[132:135], v242 offset:2048
	ds_read_b128 v[140:143], v240 offset:2048
	ds_read_b128 v[144:147], v240 offset:4096
	ds_read_b128 v[148:151], v240 offset:6144
	ds_read_b128 v[152:155], v243
	ds_read_b128 v[156:159], v243 offset:2048
	ds_read_b128 v[160:163], v241
	ds_read_b128 v[164:167], v241 offset:2048
	ds_read_b128 v[168:171], v241 offset:4096
	ds_read_b128 v[172:175], v241 offset:6144
	s_waitcnt lgkmcnt(10)
	v_mfma_f32_32x32x16_bf16 v[112:127], v[128:131], v[136:139], v[112:127]
	s_waitcnt lgkmcnt(9)
	v_mfma_f32_32x32x16_bf16 v[96:111], v[132:135], v[136:139], v[96:111]
	s_waitcnt lgkmcnt(8)
	v_mfma_f32_32x32x16_bf16 v[80:95], v[128:131], v[140:143], v[80:95]
	v_mfma_f32_32x32x16_bf16 v[64:79], v[132:135], v[140:143], v[64:79]
	s_waitcnt lgkmcnt(7)
	v_mfma_f32_32x32x16_bf16 v[48:63], v[128:131], v[144:147], v[48:63]
	v_mfma_f32_32x32x16_bf16 v[32:47], v[132:135], v[144:147], v[32:47]
	s_waitcnt lgkmcnt(6)
	v_mfma_f32_32x32x16_bf16 v[16:31], v[128:131], v[148:151], v[16:31]
	v_mfma_f32_32x32x16_bf16 v[0:15], v[132:135], v[148:151], v[0:15]
	s_waitcnt lgkmcnt(3)
	v_mfma_f32_32x32x16_bf16 v[112:127], v[152:155], v[160:163], v[112:127]
	v_mfma_f32_32x32x16_bf16 v[96:111], v[156:159], v[160:163], v[96:111]
	s_waitcnt lgkmcnt(2)
	v_mfma_f32_32x32x16_bf16 v[80:95], v[152:155], v[164:167], v[80:95]
	v_mfma_f32_32x32x16_bf16 v[64:79], v[156:159], v[164:167], v[64:79]
	s_waitcnt lgkmcnt(1)
	v_mfma_f32_32x32x16_bf16 v[48:63], v[152:155], v[168:171], v[48:63]
	s_mov_b32 s32, 0x6000
	s_cmp_eq_u32 s49, 0xc000
	s_cselect_b32 s32, 0xffff4000, s32
	s_add_u32 s49, s49, s32
	v_add_u32_e32 v240, s32, v240
	v_add_u32_e32 v241, s32, v241
	v_add_u32_e32 v242, s32, v242
	v_add_u32_e32 v243, s32, v243
	v_mfma_f32_32x32x16_bf16 v[32:47], v[156:159], v[168:171], v[32:47]
	s_waitcnt lgkmcnt(0)
	v_mfma_f32_32x32x16_bf16 v[16:31], v[152:155], v[172:175], v[16:31]
	v_mfma_f32_32x32x16_bf16 v[0:15], v[156:159], v[172:175], v[0:15]
	s_add_u32 s17, s17, 1
	s_waitcnt vmcnt(0)
	s_cmp_lt_u32 s17, 32
	s_barrier
	s_cbranch_scc1 .Lp7_tail
	s_branch .LBB0_74

.LBB0_106:
	s_and_b32 s2, s2, 7
	v_readlane_b32 s4, v251, 7
	s_or_b32 s16, s2, s4
	s_lshl_b32 s4, s15, 7
	s_lshl_b32 s14, s16, 19
	v_mov_b32_e32 v56, v200
	s_add_u32 s6, s20, s14
	s_mov_b32 s5, s3
	s_addc_u32 s7, s21, 0
	v_ashrrev_i32_e32 v36, 2, v56
	v_lshlrev_b32_e32 v0, 3, v56
	s_lshl_b64 s[8:9], s[4:5], 11
	v_readlane_b32 s10, v249, 19
	s_waitcnt vmcnt(0)
	v_and_b32_e32 v188, 24, v0
	v_add_u32_e32 v44, 0x80, v36
	v_readlane_b32 s11, v249, 20
	s_add_u32 s8, s10, s8
	v_lshlrev_b32_e32 v196, 1, v188
	v_add_u32_e32 v40, 64, v36
	v_ashrrev_i32_e32 v45, 31, v44
	v_add_u32_e32 v48, 0xc0, v36
	s_addc_u32 s9, s11, s9
	v_lshl_add_u64 v[176:177], s[6:7], 0, v[196:197]
	v_ashrrev_i32_e32 v37, 31, v36
	v_ashrrev_i32_e32 v41, 31, v40
	v_lshlrev_b64 v[4:5], 11, v[44:45]
	v_ashrrev_i32_e32 v49, 31, v48
	v_lshlrev_b64 v[0:1], 11, v[36:37]
	v_lshlrev_b64 v[2:3], 11, v[40:41]
	v_lshl_add_u64 v[46:47], v[176:177], 0, v[4:5]
	v_lshlrev_b64 v[4:5], 11, v[48:49]
	v_lshl_add_u64 v[178:179], s[8:9], 0, v[196:197]
	v_lshl_add_u64 v[38:39], v[176:177], 0, v[0:1]
	v_lshl_add_u64 v[42:43], v[176:177], 0, v[2:3]
	v_lshl_add_u64 v[50:51], v[176:177], 0, v[4:5]
	v_lshl_add_u64 v[52:53], v[178:179], 0, v[0:1]
	v_lshl_add_u64 v[54:55], v[178:179], 0, v[2:3]
	v_and_b32_e32 v192, 63, v200
	v_readfirstlane_b32 s44, v200
	v_lshrrev_b32_e32 v193, 2, v192
	v_and_b32_e32 v194, 3, v192
	v_lshrrev_b32_e32 v201, 4, v192
	s_lshr_b32 s44, s44, 6
	v_xor_b32_e32 v206, v194, v201
	v_lshlrev_b32_e32 v206, 4, v206
	s_lshl_b32 s32, s44, 6
	v_add_u32_e32 v212, s32, v193
	v_lshlrev_b32_e32 v212, 11, v212
	v_add_u32_e32 v234, v212, v206
	v_add_u32_e32 v235, 0x8000, v234
	v_add_u32_e32 v236, 0x10000, v234
	v_add_u32_e32 v237, 0x18000, v234
	s_lshl_b32 s32, s44, 5
	v_add_u32_e32 v212, s32, v193
	v_lshlrev_b32_e32 v212, 11, v212
	v_add_u32_e32 v238, v212, v206
	v_add_u32_e32 v239, 0x8000, v238
	v_and_b32_e32 v193, 31, v192
	v_lshrrev_b32_e32 v194, 5, v192
	v_bfe_u32 v201, v192, 2, 2
	v_xor_b32_e32 v206, v194, v201
	v_lshlrev_b32_e32 v206, 4, v206
	v_lshl_add_u32 v206, v193, 6, v206
	s_lshr_b32 s32, s44, 1
	s_lshl_b32 s32, s32, 13
	v_add_u32_e32 v240, s32, v206
	v_xor_b32_e32 v241, 32, v240
	s_and_b32 s32, s44, 1
	s_lshl_b32 s32, s32, 12
	s_add_u32 s32, s32, 0x4000
	v_add_u32_e32 v242, s32, v206
	v_xor_b32_e32 v243, 32, v242
	s_lshl_b32 s46, s44, 12
	s_lshl_b32 s47, s44, 11
	s_add_u32 s47, s47, 0x4000
	s_mov_b32 s40, s6
	s_mov_b32 s41, s7
	s_mov_b32 s42, s8
	s_mov_b32 s43, s9
	s_add_u32 m0, s46, 0x0
	s_nop 0
	global_load_lds_dwordx4 v234, s[40:41]
	s_add_u32 m0, m0, 0x400
	s_nop 0
	global_load_lds_dwordx4 v235, s[40:41]
	s_add_u32 m0, m0, 0x400
	s_nop 0
	global_load_lds_dwordx4 v236, s[40:41]
	s_add_u32 m0, m0, 0x400
	s_nop 0
	global_load_lds_dwordx4 v237, s[40:41]
	s_add_u32 m0, s47, 0x0
	s_nop 0
	global_load_lds_dwordx4 v238, s[42:43]
	s_add_u32 m0, m0, 0x400
	s_nop 0
	global_load_lds_dwordx4 v239, s[42:43]
	s_add_u32 s40, s40, 64
	s_addc_u32 s41, s41, 0
	s_add_u32 s42, s42, 64
	s_addc_u32 s43, s43, 0
	s_add_u32 m0, s46, 0x6000
	s_nop 0
	global_load_lds_dwordx4 v234, s[40:41]
	s_add_u32 m0, m0, 0x400
	s_nop 0
	global_load_lds_dwordx4 v235, s[40:41]
	s_add_u32 m0, m0, 0x400
	s_nop 0
	global_load_lds_dwordx4 v236, s[40:41]
	s_add_u32 m0, m0, 0x400
	s_nop 0
	global_load_lds_dwordx4 v237, s[40:41]
	s_add_u32 m0, s47, 0x6000
	s_nop 0
	global_load_lds_dwordx4 v238, s[42:43]
	s_add_u32 m0, m0, 0x400
	s_nop 0
	global_load_lds_dwordx4 v239, s[42:43]
	s_add_u32 s40, s40, 64
	s_addc_u32 s41, s41, 0
	s_add_u32 s42, s42, 64
	s_addc_u32 s43, s43, 0
	s_mov_b32 s45, 0xc000
	s_mov_b32 s49, 0
	v_and_b32_e32 v57, 0xfffff9f, v56
	v_lshrrev_b32_e32 v58, 1, v56
	v_and_b32_e32 v56, 0x5f, v56
	s_movk_i32 s2, 0x50
	v_and_b32_e32 v58, 16, v58
	v_mad_u32_u24 v56, v56, s2, 0
	v_mul_lo_u32 v59, v36, s2
	v_mul_lo_u32 v57, v57, s2
	v_add_u32_e32 v189, v56, v58
	v_add_u32_e32 v56, 0, v196
	v_mov_b32_e32 v0, 0
	v_lshlrev_b64 v[36:37], 10, v[36:37]
	v_add_u32_e32 v57, 0, v57
	v_lshlrev_b64 v[40:41], 10, v[40:41]
	v_lshlrev_b64 v[44:45], 10, v[44:45]
	v_lshlrev_b64 v[48:49], 10, v[48:49]
	v_add_u32_e32 v191, v56, v59
	s_mov_b32 s5, 64
	s_mov_b32 s17, 0
	v_mov_b32_e32 v1, v0
	v_mov_b32_e32 v2, v0
	v_mov_b32_e32 v3, v0
	v_mov_b32_e32 v4, v0
	v_mov_b32_e32 v5, v0
	v_mov_b32_e32 v6, v0
	v_mov_b32_e32 v7, v0
	v_mov_b32_e32 v8, v0
	v_mov_b32_e32 v9, v0
	v_mov_b32_e32 v10, v0
	v_mov_b32_e32 v11, v0
	v_lshlrev_b64 v[180:181], 1, v[36:37]
	v_add_u32_e32 v190, v57, v58
	v_lshlrev_b64 v[182:183], 1, v[40:41]
	v_lshlrev_b64 v[184:185], 1, v[44:45]
	v_lshlrev_b64 v[186:187], 1, v[48:49]
	v_mov_b32_e32 v36, v0
	v_mov_b32_e32 v37, v0
	v_mov_b32_e32 v38, v0
	v_mov_b32_e32 v39, v0
	v_mov_b32_e32 v40, v0
	v_mov_b32_e32 v41, v0
	v_mov_b32_e32 v42, v0
	v_mov_b32_e32 v12, v0
	v_mov_b32_e32 v13, v0
	v_mov_b32_e32 v14, v0
	v_mov_b32_e32 v15, v0
	v_mov_b32_e32 v16, v0
	v_mov_b32_e32 v17, v0
	v_mov_b32_e32 v18, v0
	v_mov_b32_e32 v19, v0
	v_mov_b32_e32 v20, v0
	v_mov_b32_e32 v21, v0
	v_mov_b32_e32 v22, v0
	v_mov_b32_e32 v23, v0
	v_mov_b32_e32 v24, v0
	v_mov_b32_e32 v25, v0
	v_mov_b32_e32 v26, v0
	v_mov_b32_e32 v27, v0
	v_mov_b32_e32 v28, v0
	v_mov_b32_e32 v29, v0
	v_mov_b32_e32 v30, v0
	v_mov_b32_e32 v31, v0
	v_mov_b32_e32 v32, v0
	v_mov_b32_e32 v33, v0
	v_mov_b32_e32 v34, v0
	v_mov_b32_e32 v35, v0
	v_mov_b32_e32 v43, v0
	v_mov_b32_e32 v44, v0
	v_mov_b32_e32 v45, v0
	v_mov_b32_e32 v46, v0
	v_mov_b32_e32 v47, v0
	v_mov_b32_e32 v48, v0
	v_mov_b32_e32 v49, v0
	v_mov_b32_e32 v50, v0
	v_mov_b32_e32 v51, v0
	v_mov_b32_e32 v52, v0
	v_mov_b32_e32 v53, v0
	v_mov_b32_e32 v54, v0
	v_mov_b32_e32 v55, v0
	v_mov_b32_e32 v56, v0
	v_mov_b32_e32 v57, v0
	v_mov_b32_e32 v58, v0
	v_mov_b32_e32 v59, v0
	v_mov_b32_e32 v60, v0
	v_mov_b32_e32 v61, v0
	v_mov_b32_e32 v62, v0
	v_mov_b32_e32 v63, v0
	v_mov_b32_e32 v64, v0
	v_mov_b32_e32 v65, v0
	v_mov_b32_e32 v66, v0
	v_mov_b32_e32 v67, v0
	v_mov_b32_e32 v68, v0
	v_mov_b32_e32 v69, v0
	v_mov_b32_e32 v70, v0
	v_mov_b32_e32 v71, v0
	v_mov_b32_e32 v72, v0
	v_mov_b32_e32 v73, v0
	v_mov_b32_e32 v74, v0
	v_mov_b32_e32 v75, v0
	v_mov_b32_e32 v76, v0
	v_mov_b32_e32 v77, v0
	v_mov_b32_e32 v78, v0
	v_mov_b32_e32 v79, v0
	v_mov_b32_e32 v80, v0
	v_mov_b32_e32 v81, v0
	v_mov_b32_e32 v82, v0
	v_mov_b32_e32 v83, v0
	v_mov_b32_e32 v84, v0
	v_mov_b32_e32 v85, v0
	v_mov_b32_e32 v86, v0
	v_mov_b32_e32 v87, v0
	v_mov_b32_e32 v88, v0
	v_mov_b32_e32 v89, v0
	v_mov_b32_e32 v90, v0
	v_mov_b32_e32 v91, v0
	v_mov_b32_e32 v92, v0
	v_mov_b32_e32 v93, v0
	v_mov_b32_e32 v94, v0
	v_mov_b32_e32 v95, v0
	v_mov_b32_e32 v96, v0
	v_mov_b32_e32 v97, v0
	v_mov_b32_e32 v98, v0
	v_mov_b32_e32 v99, v0
	v_mov_b32_e32 v100, v0
	v_mov_b32_e32 v101, v0
	v_mov_b32_e32 v102, v0
	v_mov_b32_e32 v103, v0
	v_mov_b32_e32 v104, v0
	v_mov_b32_e32 v105, v0
	v_mov_b32_e32 v106, v0
	v_mov_b32_e32 v107, v0
	v_mov_b32_e32 v108, v0
	v_mov_b32_e32 v109, v0
	v_mov_b32_e32 v110, v0
	v_mov_b32_e32 v111, v0
	v_mov_b32_e32 v112, v0
	v_mov_b32_e32 v113, v0
	v_mov_b32_e32 v114, v0
	v_mov_b32_e32 v115, v0
	v_mov_b32_e32 v116, v0
	v_mov_b32_e32 v117, v0
	v_mov_b32_e32 v118, v0
	v_mov_b32_e32 v119, v0
	v_mov_b32_e32 v120, v0
	v_mov_b32_e32 v121, v0
	v_mov_b32_e32 v122, v0
	v_mov_b32_e32 v123, v0
	v_mov_b32_e32 v124, v0
	v_mov_b32_e32 v125, v0
	v_mov_b32_e32 v126, v0
	v_mov_b32_e32 v127, v0
	s_waitcnt vmcnt(6)
	s_waitcnt lgkmcnt(0)
	s_barrier
	s_branch .LBB0_108
